# G1B gate-sigmoid epilogue hand-rewritten with packed f32 ops (fma with pre-scaled bias, exp2, rcp), same math in f32
# baseline (speedup 1.0000x reference)
.LBB0_1103:
	s_lshl_b32 s0, s11, 8
	s_or_b32 s0, s0, s73
	v_lshl_add_u32 v158, v160, 3, s0
	v_ashrrev_i32_e32 v159, 31, v158
	s_waitcnt lgkmcnt(0)
	v_lshl_add_u64 v[168:169], v[158:159], 2, s[16:17]
	global_load_dwordx4 v[170:173], v[168:169], off
	global_load_dwordx4 v[174:177], v[168:169], off offset:16
	global_load_dwordx4 v[178:181], v[168:169], off offset:128
	global_load_dwordx4 v[182:185], v[168:169], off offset:144
	s_lshl_b32 s0, s10, 8
	s_add_i32 s0, s0, s71
	v_add_u32_e32 v214, s0, v161
	v_ashrrev_i32_e32 v215, 31, v214
	v_lshlrev_b64 v[166:167], 13, v[214:215]
	v_lshl_add_u64 v[166:167], s[24:25], 0, v[166:167]
	v_lshl_add_u64 v[166:167], v[158:159], 1, v[166:167]
	v_mov_b32_e32 v186, 0xbfb8aa3b
	v_mov_b32_e32 v187, 0xbfb8aa3b
	v_mov_b32_e32 v188, 1.0
	v_mov_b32_e32 v189, 1.0
	s_waitcnt vmcnt(0)
	v_pk_mul_f32 v[170:171], v[170:171], v[186:187]
	v_pk_mul_f32 v[172:173], v[172:173], v[186:187]
	v_pk_mul_f32 v[174:175], v[174:175], v[186:187]
	v_pk_mul_f32 v[176:177], v[176:177], v[186:187]
	v_pk_mul_f32 v[178:179], v[178:179], v[186:187]
	v_pk_mul_f32 v[180:181], v[180:181], v[186:187]
	v_pk_mul_f32 v[182:183], v[182:183], v[186:187]
	v_pk_mul_f32 v[184:185], v[184:185], v[186:187]
	v_pk_fma_f32 v[190:191], v[140:141], v[186:187], v[170:171]
	v_pk_fma_f32 v[192:193], v[142:143], v[186:187], v[172:173]
	v_pk_fma_f32 v[194:195], v[136:137], v[186:187], v[174:175]
	v_pk_fma_f32 v[196:197], v[138:139], v[186:187], v[176:177]
	v_pk_fma_f32 v[198:199], v[132:133], v[186:187], v[178:179]
	v_pk_fma_f32 v[200:201], v[134:135], v[186:187], v[180:181]
	v_pk_fma_f32 v[202:203], v[128:129], v[186:187], v[182:183]
	v_pk_fma_f32 v[204:205], v[130:131], v[186:187], v[184:185]
	v_exp_f32_e32 v190, v190
	v_exp_f32_e32 v191, v191
	v_exp_f32_e32 v192, v192
	v_exp_f32_e32 v193, v193
	v_exp_f32_e32 v194, v194
	v_exp_f32_e32 v195, v195
	v_exp_f32_e32 v196, v196
	v_exp_f32_e32 v197, v197
	v_exp_f32_e32 v198, v198
	v_exp_f32_e32 v199, v199
	v_exp_f32_e32 v200, v200
	v_exp_f32_e32 v201, v201
	v_exp_f32_e32 v202, v202
	v_exp_f32_e32 v203, v203
	v_exp_f32_e32 v204, v204
	v_exp_f32_e32 v205, v205
	s_nop 0
	v_pk_add_f32 v[190:191], v[190:191], v[188:189]
	v_pk_add_f32 v[192:193], v[192:193], v[188:189]
	v_pk_add_f32 v[194:195], v[194:195], v[188:189]
	v_pk_add_f32 v[196:197], v[196:197], v[188:189]
	v_pk_add_f32 v[198:199], v[198:199], v[188:189]
	v_pk_add_f32 v[200:201], v[200:201], v[188:189]
	v_pk_add_f32 v[202:203], v[202:203], v[188:189]
	v_pk_add_f32 v[204:205], v[204:205], v[188:189]
	v_rcp_f32_e32 v190, v190
	v_rcp_f32_e32 v191, v191
	v_rcp_f32_e32 v192, v192
	v_rcp_f32_e32 v193, v193
	v_rcp_f32_e32 v194, v194
	v_rcp_f32_e32 v195, v195
	v_rcp_f32_e32 v196, v196
	v_rcp_f32_e32 v197, v197
	v_rcp_f32_e32 v198, v198
	v_rcp_f32_e32 v199, v199
	v_rcp_f32_e32 v200, v200
	v_rcp_f32_e32 v201, v201
	v_rcp_f32_e32 v202, v202
	v_rcp_f32_e32 v203, v203
	v_rcp_f32_e32 v204, v204
	v_rcp_f32_e32 v205, v205
	s_nop 0
	v_cvt_pk_bf16_f32 v206, v190, v191
	v_cvt_pk_bf16_f32 v207, v192, v193
	v_cvt_pk_bf16_f32 v208, v194, v195
	v_cvt_pk_bf16_f32 v209, v196, v197
	v_cvt_pk_bf16_f32 v210, v198, v199
	v_cvt_pk_bf16_f32 v211, v200, v201
	v_cvt_pk_bf16_f32 v212, v202, v203
	v_cvt_pk_bf16_f32 v213, v204, v205
	global_store_dwordx4 v[166:167], v[206:209], off
	global_store_dwordx4 v[166:167], v[210:213], off offset:64
	s_nop 1
	s_mov_b64 s[98:99], 0x20000
	v_lshl_add_u64 v[166:167], v[166:167], 0, s[98:99]
	v_pk_fma_f32 v[190:191], v[124:125], v[186:187], v[170:171]
	v_pk_fma_f32 v[192:193], v[126:127], v[186:187], v[172:173]
	v_pk_fma_f32 v[194:195], v[120:121], v[186:187], v[174:175]
	v_pk_fma_f32 v[196:197], v[122:123], v[186:187], v[176:177]
	v_pk_fma_f32 v[198:199], v[116:117], v[186:187], v[178:179]
	v_pk_fma_f32 v[200:201], v[118:119], v[186:187], v[180:181]
	v_pk_fma_f32 v[202:203], v[112:113], v[186:187], v[182:183]
	v_pk_fma_f32 v[204:205], v[114:115], v[186:187], v[184:185]
	v_exp_f32_e32 v190, v190
	v_exp_f32_e32 v191, v191
	v_exp_f32_e32 v192, v192
	v_exp_f32_e32 v193, v193
	v_exp_f32_e32 v194, v194
	v_exp_f32_e32 v195, v195
	v_exp_f32_e32 v196, v196
	v_exp_f32_e32 v197, v197
	v_exp_f32_e32 v198, v198
	v_exp_f32_e32 v199, v199
	v_exp_f32_e32 v200, v200
	v_exp_f32_e32 v201, v201
	v_exp_f32_e32 v202, v202
	v_exp_f32_e32 v203, v203
	v_exp_f32_e32 v204, v204
	v_exp_f32_e32 v205, v205
	s_nop 0
	v_pk_add_f32 v[190:191], v[190:191], v[188:189]
	v_pk_add_f32 v[192:193], v[192:193], v[188:189]
	v_pk_add_f32 v[194:195], v[194:195], v[188:189]
	v_pk_add_f32 v[196:197], v[196:197], v[188:189]
	v_pk_add_f32 v[198:199], v[198:199], v[188:189]
	v_pk_add_f32 v[200:201], v[200:201], v[188:189]
	v_pk_add_f32 v[202:203], v[202:203], v[188:189]
	v_pk_add_f32 v[204:205], v[204:205], v[188:189]
	v_rcp_f32_e32 v190, v190
	v_rcp_f32_e32 v191, v191
	v_rcp_f32_e32 v192, v192
	v_rcp_f32_e32 v193, v193
	v_rcp_f32_e32 v194, v194
	v_rcp_f32_e32 v195, v195
	v_rcp_f32_e32 v196, v196
	v_rcp_f32_e32 v197, v197
	v_rcp_f32_e32 v198, v198
	v_rcp_f32_e32 v199, v199
	v_rcp_f32_e32 v200, v200
	v_rcp_f32_e32 v201, v201
	v_rcp_f32_e32 v202, v202
	v_rcp_f32_e32 v203, v203
	v_rcp_f32_e32 v204, v204
	v_rcp_f32_e32 v205, v205
	s_nop 0
	v_cvt_pk_bf16_f32 v206, v190, v191
	v_cvt_pk_bf16_f32 v207, v192, v193
	v_cvt_pk_bf16_f32 v208, v194, v195
	v_cvt_pk_bf16_f32 v209, v196, v197
	v_cvt_pk_bf16_f32 v210, v198, v199
	v_cvt_pk_bf16_f32 v211, v200, v201
	v_cvt_pk_bf16_f32 v212, v202, v203
	v_cvt_pk_bf16_f32 v213, v204, v205
	global_store_dwordx4 v[166:167], v[206:209], off
	global_store_dwordx4 v[166:167], v[210:213], off offset:64
	s_nop 1
	s_mov_b64 s[98:99], 0x20000
	v_lshl_add_u64 v[166:167], v[166:167], 0, s[98:99]
	v_pk_fma_f32 v[190:191], v[108:109], v[186:187], v[170:171]
	v_pk_fma_f32 v[192:193], v[110:111], v[186:187], v[172:173]
	v_pk_fma_f32 v[194:195], v[104:105], v[186:187], v[174:175]
	v_pk_fma_f32 v[196:197], v[106:107], v[186:187], v[176:177]
	v_pk_fma_f32 v[198:199], v[100:101], v[186:187], v[178:179]
	v_pk_fma_f32 v[200:201], v[102:103], v[186:187], v[180:181]
	v_pk_fma_f32 v[202:203], v[96:97], v[186:187], v[182:183]
	v_pk_fma_f32 v[204:205], v[98:99], v[186:187], v[184:185]
	v_exp_f32_e32 v190, v190
	v_exp_f32_e32 v191, v191
	v_exp_f32_e32 v192, v192
	v_exp_f32_e32 v193, v193
	v_exp_f32_e32 v194, v194
	v_exp_f32_e32 v195, v195
	v_exp_f32_e32 v196, v196
	v_exp_f32_e32 v197, v197
	v_exp_f32_e32 v198, v198
	v_exp_f32_e32 v199, v199
	v_exp_f32_e32 v200, v200
	v_exp_f32_e32 v201, v201
	v_exp_f32_e32 v202, v202
	v_exp_f32_e32 v203, v203
	v_exp_f32_e32 v204, v204
	v_exp_f32_e32 v205, v205
	s_nop 0
	v_pk_add_f32 v[190:191], v[190:191], v[188:189]
	v_pk_add_f32 v[192:193], v[192:193], v[188:189]
	v_pk_add_f32 v[194:195], v[194:195], v[188:189]
	v_pk_add_f32 v[196:197], v[196:197], v[188:189]
	v_pk_add_f32 v[198:199], v[198:199], v[188:189]
	v_pk_add_f32 v[200:201], v[200:201], v[188:189]
	v_pk_add_f32 v[202:203], v[202:203], v[188:189]
	v_pk_add_f32 v[204:205], v[204:205], v[188:189]
	v_rcp_f32_e32 v190, v190
	v_rcp_f32_e32 v191, v191
	v_rcp_f32_e32 v192, v192
	v_rcp_f32_e32 v193, v193
	v_rcp_f32_e32 v194, v194
	v_rcp_f32_e32 v195, v195
	v_rcp_f32_e32 v196, v196
	v_rcp_f32_e32 v197, v197
	v_rcp_f32_e32 v198, v198
	v_rcp_f32_e32 v199, v199
	v_rcp_f32_e32 v200, v200
	v_rcp_f32_e32 v201, v201
	v_rcp_f32_e32 v202, v202
	v_rcp_f32_e32 v203, v203
	v_rcp_f32_e32 v204, v204
	v_rcp_f32_e32 v205, v205
	s_nop 0
	v_cvt_pk_bf16_f32 v206, v190, v191
	v_cvt_pk_bf16_f32 v207, v192, v193
	v_cvt_pk_bf16_f32 v208, v194, v195
	v_cvt_pk_bf16_f32 v209, v196, v197
	v_cvt_pk_bf16_f32 v210, v198, v199
	v_cvt_pk_bf16_f32 v211, v200, v201
	v_cvt_pk_bf16_f32 v212, v202, v203
	v_cvt_pk_bf16_f32 v213, v204, v205
	global_store_dwordx4 v[166:167], v[206:209], off
	global_store_dwordx4 v[166:167], v[210:213], off offset:64
	s_nop 1
	s_mov_b64 s[98:99], 0x20000
	v_lshl_add_u64 v[166:167], v[166:167], 0, s[98:99]
	v_pk_fma_f32 v[190:191], v[92:93], v[186:187], v[170:171]
	v_pk_fma_f32 v[192:193], v[94:95], v[186:187], v[172:173]
	v_pk_fma_f32 v[194:195], v[88:89], v[186:187], v[174:175]
	v_pk_fma_f32 v[196:197], v[90:91], v[186:187], v[176:177]
	v_pk_fma_f32 v[198:199], v[84:85], v[186:187], v[178:179]
	v_pk_fma_f32 v[200:201], v[86:87], v[186:187], v[180:181]
	v_pk_fma_f32 v[202:203], v[80:81], v[186:187], v[182:183]
	v_pk_fma_f32 v[204:205], v[82:83], v[186:187], v[184:185]
	v_exp_f32_e32 v190, v190
	v_exp_f32_e32 v191, v191
	v_exp_f32_e32 v192, v192
	v_exp_f32_e32 v193, v193
	v_exp_f32_e32 v194, v194
	v_exp_f32_e32 v195, v195
	v_exp_f32_e32 v196, v196
	v_exp_f32_e32 v197, v197
	v_exp_f32_e32 v198, v198
	v_exp_f32_e32 v199, v199
	v_exp_f32_e32 v200, v200
	v_exp_f32_e32 v201, v201
	v_exp_f32_e32 v202, v202
	v_exp_f32_e32 v203, v203
	v_exp_f32_e32 v204, v204
	v_exp_f32_e32 v205, v205
	s_nop 0
	v_pk_add_f32 v[190:191], v[190:191], v[188:189]
	v_pk_add_f32 v[192:193], v[192:193], v[188:189]
	v_pk_add_f32 v[194:195], v[194:195], v[188:189]
	v_pk_add_f32 v[196:197], v[196:197], v[188:189]
	v_pk_add_f32 v[198:199], v[198:199], v[188:189]
	v_pk_add_f32 v[200:201], v[200:201], v[188:189]
	v_pk_add_f32 v[202:203], v[202:203], v[188:189]
	v_pk_add_f32 v[204:205], v[204:205], v[188:189]
	v_rcp_f32_e32 v190, v190
	v_rcp_f32_e32 v191, v191
	v_rcp_f32_e32 v192, v192
	v_rcp_f32_e32 v193, v193
	v_rcp_f32_e32 v194, v194
	v_rcp_f32_e32 v195, v195
	v_rcp_f32_e32 v196, v196
	v_rcp_f32_e32 v197, v197
	v_rcp_f32_e32 v198, v198
	v_rcp_f32_e32 v199, v199
	v_rcp_f32_e32 v200, v200
	v_rcp_f32_e32 v201, v201
	v_rcp_f32_e32 v202, v202
	v_rcp_f32_e32 v203, v203
	v_rcp_f32_e32 v204, v204
	v_rcp_f32_e32 v205, v205
	s_nop 0
	v_cvt_pk_bf16_f32 v206, v190, v191
	v_cvt_pk_bf16_f32 v207, v192, v193
	v_cvt_pk_bf16_f32 v208, v194, v195
	v_cvt_pk_bf16_f32 v209, v196, v197
	v_cvt_pk_bf16_f32 v210, v198, v199
	v_cvt_pk_bf16_f32 v211, v200, v201
	v_cvt_pk_bf16_f32 v212, v202, v203
	v_cvt_pk_bf16_f32 v213, v204, v205
	global_store_dwordx4 v[166:167], v[206:209], off
	global_store_dwordx4 v[166:167], v[210:213], off offset:64
	s_nop 1
	s_mov_b64 s[98:99], 0xa0000
	v_lshl_add_u64 v[166:167], v[166:167], 0, s[98:99]
	v_pk_fma_f32 v[190:191], v[76:77], v[186:187], v[170:171]
	v_pk_fma_f32 v[192:193], v[78:79], v[186:187], v[172:173]
	v_pk_fma_f32 v[194:195], v[72:73], v[186:187], v[174:175]
	v_pk_fma_f32 v[196:197], v[74:75], v[186:187], v[176:177]
	v_pk_fma_f32 v[198:199], v[64:65], v[186:187], v[178:179]
	v_pk_fma_f32 v[200:201], v[66:67], v[186:187], v[180:181]
	v_pk_fma_f32 v[202:203], v[56:57], v[186:187], v[182:183]
	v_pk_fma_f32 v[204:205], v[58:59], v[186:187], v[184:185]
	v_exp_f32_e32 v190, v190
	v_exp_f32_e32 v191, v191
	v_exp_f32_e32 v192, v192
	v_exp_f32_e32 v193, v193
	v_exp_f32_e32 v194, v194
	v_exp_f32_e32 v195, v195
	v_exp_f32_e32 v196, v196
	v_exp_f32_e32 v197, v197
	v_exp_f32_e32 v198, v198
	v_exp_f32_e32 v199, v199
	v_exp_f32_e32 v200, v200
	v_exp_f32_e32 v201, v201
	v_exp_f32_e32 v202, v202
	v_exp_f32_e32 v203, v203
	v_exp_f32_e32 v204, v204
	v_exp_f32_e32 v205, v205
	s_nop 0
	v_pk_add_f32 v[190:191], v[190:191], v[188:189]
	v_pk_add_f32 v[192:193], v[192:193], v[188:189]
	v_pk_add_f32 v[194:195], v[194:195], v[188:189]
	v_pk_add_f32 v[196:197], v[196:197], v[188:189]
	v_pk_add_f32 v[198:199], v[198:199], v[188:189]
	v_pk_add_f32 v[200:201], v[200:201], v[188:189]
	v_pk_add_f32 v[202:203], v[202:203], v[188:189]
	v_pk_add_f32 v[204:205], v[204:205], v[188:189]
	v_rcp_f32_e32 v190, v190
	v_rcp_f32_e32 v191, v191
	v_rcp_f32_e32 v192, v192
	v_rcp_f32_e32 v193, v193
	v_rcp_f32_e32 v194, v194
	v_rcp_f32_e32 v195, v195
	v_rcp_f32_e32 v196, v196
	v_rcp_f32_e32 v197, v197
	v_rcp_f32_e32 v198, v198
	v_rcp_f32_e32 v199, v199
	v_rcp_f32_e32 v200, v200
	v_rcp_f32_e32 v201, v201
	v_rcp_f32_e32 v202, v202
	v_rcp_f32_e32 v203, v203
	v_rcp_f32_e32 v204, v204
	v_rcp_f32_e32 v205, v205
	s_nop 0
	v_cvt_pk_bf16_f32 v206, v190, v191
	v_cvt_pk_bf16_f32 v207, v192, v193
	v_cvt_pk_bf16_f32 v208, v194, v195
	v_cvt_pk_bf16_f32 v209, v196, v197
	v_cvt_pk_bf16_f32 v210, v198, v199
	v_cvt_pk_bf16_f32 v211, v200, v201
	v_cvt_pk_bf16_f32 v212, v202, v203
	v_cvt_pk_bf16_f32 v213, v204, v205
	global_store_dwordx4 v[166:167], v[206:209], off
	global_store_dwordx4 v[166:167], v[210:213], off offset:64
	s_nop 1
	s_mov_b64 s[98:99], 0x20000
	v_lshl_add_u64 v[166:167], v[166:167], 0, s[98:99]
	v_pk_fma_f32 v[190:191], v[48:49], v[186:187], v[170:171]
	v_pk_fma_f32 v[192:193], v[50:51], v[186:187], v[172:173]
	v_pk_fma_f32 v[194:195], v[40:41], v[186:187], v[174:175]
	v_pk_fma_f32 v[196:197], v[42:43], v[186:187], v[176:177]
	v_pk_fma_f32 v[198:199], v[36:37], v[186:187], v[178:179]
	v_pk_fma_f32 v[200:201], v[38:39], v[186:187], v[180:181]
	v_pk_fma_f32 v[202:203], v[32:33], v[186:187], v[182:183]
	v_pk_fma_f32 v[204:205], v[34:35], v[186:187], v[184:185]
	v_exp_f32_e32 v190, v190
	v_exp_f32_e32 v191, v191
	v_exp_f32_e32 v192, v192
	v_exp_f32_e32 v193, v193
	v_exp_f32_e32 v194, v194
	v_exp_f32_e32 v195, v195
	v_exp_f32_e32 v196, v196
	v_exp_f32_e32 v197, v197
	v_exp_f32_e32 v198, v198
	v_exp_f32_e32 v199, v199
	v_exp_f32_e32 v200, v200
	v_exp_f32_e32 v201, v201
	v_exp_f32_e32 v202, v202
	v_exp_f32_e32 v203, v203
	v_exp_f32_e32 v204, v204
	v_exp_f32_e32 v205, v205
	s_nop 0
	v_pk_add_f32 v[190:191], v[190:191], v[188:189]
	v_pk_add_f32 v[192:193], v[192:193], v[188:189]
	v_pk_add_f32 v[194:195], v[194:195], v[188:189]
	v_pk_add_f32 v[196:197], v[196:197], v[188:189]
	v_pk_add_f32 v[198:199], v[198:199], v[188:189]
	v_pk_add_f32 v[200:201], v[200:201], v[188:189]
	v_pk_add_f32 v[202:203], v[202:203], v[188:189]
	v_pk_add_f32 v[204:205], v[204:205], v[188:189]
	v_rcp_f32_e32 v190, v190
	v_rcp_f32_e32 v191, v191
	v_rcp_f32_e32 v192, v192
	v_rcp_f32_e32 v193, v193
	v_rcp_f32_e32 v194, v194
	v_rcp_f32_e32 v195, v195
	v_rcp_f32_e32 v196, v196
	v_rcp_f32_e32 v197, v197
	v_rcp_f32_e32 v198, v198
	v_rcp_f32_e32 v199, v199
	v_rcp_f32_e32 v200, v200
	v_rcp_f32_e32 v201, v201
	v_rcp_f32_e32 v202, v202
	v_rcp_f32_e32 v203, v203
	v_rcp_f32_e32 v204, v204
	v_rcp_f32_e32 v205, v205
	s_nop 0
	v_cvt_pk_bf16_f32 v206, v190, v191
	v_cvt_pk_bf16_f32 v207, v192, v193
	v_cvt_pk_bf16_f32 v208, v194, v195
	v_cvt_pk_bf16_f32 v209, v196, v197
	v_cvt_pk_bf16_f32 v210, v198, v199
	v_cvt_pk_bf16_f32 v211, v200, v201
	v_cvt_pk_bf16_f32 v212, v202, v203
	v_cvt_pk_bf16_f32 v213, v204, v205
	global_store_dwordx4 v[166:167], v[206:209], off
	global_store_dwordx4 v[166:167], v[210:213], off offset:64
	s_nop 1
	s_mov_b64 s[98:99], 0x20000
	v_lshl_add_u64 v[166:167], v[166:167], 0, s[98:99]
	v_pk_fma_f32 v[190:191], v[28:29], v[186:187], v[170:171]
	v_pk_fma_f32 v[192:193], v[30:31], v[186:187], v[172:173]
	v_pk_fma_f32 v[194:195], v[24:25], v[186:187], v[174:175]
	v_pk_fma_f32 v[196:197], v[26:27], v[186:187], v[176:177]
	v_pk_fma_f32 v[198:199], v[20:21], v[186:187], v[178:179]
	v_pk_fma_f32 v[200:201], v[22:23], v[186:187], v[180:181]
	v_pk_fma_f32 v[202:203], v[16:17], v[186:187], v[182:183]
	v_pk_fma_f32 v[204:205], v[18:19], v[186:187], v[184:185]
	v_exp_f32_e32 v190, v190
	v_exp_f32_e32 v191, v191
	v_exp_f32_e32 v192, v192
	v_exp_f32_e32 v193, v193
	v_exp_f32_e32 v194, v194
	v_exp_f32_e32 v195, v195
	v_exp_f32_e32 v196, v196
	v_exp_f32_e32 v197, v197
	v_exp_f32_e32 v198, v198
	v_exp_f32_e32 v199, v199
	v_exp_f32_e32 v200, v200
	v_exp_f32_e32 v201, v201
	v_exp_f32_e32 v202, v202
	v_exp_f32_e32 v203, v203
	v_exp_f32_e32 v204, v204
	v_exp_f32_e32 v205, v205
	s_nop 0
	v_pk_add_f32 v[190:191], v[190:191], v[188:189]
	v_pk_add_f32 v[192:193], v[192:193], v[188:189]
	v_pk_add_f32 v[194:195], v[194:195], v[188:189]
	v_pk_add_f32 v[196:197], v[196:197], v[188:189]
	v_pk_add_f32 v[198:199], v[198:199], v[188:189]
	v_pk_add_f32 v[200:201], v[200:201], v[188:189]
	v_pk_add_f32 v[202:203], v[202:203], v[188:189]
	v_pk_add_f32 v[204:205], v[204:205], v[188:189]
	v_rcp_f32_e32 v190, v190
	v_rcp_f32_e32 v191, v191
	v_rcp_f32_e32 v192, v192
	v_rcp_f32_e32 v193, v193
	v_rcp_f32_e32 v194, v194
	v_rcp_f32_e32 v195, v195
	v_rcp_f32_e32 v196, v196
	v_rcp_f32_e32 v197, v197
	v_rcp_f32_e32 v198, v198
	v_rcp_f32_e32 v199, v199
	v_rcp_f32_e32 v200, v200
	v_rcp_f32_e32 v201, v201
	v_rcp_f32_e32 v202, v202
	v_rcp_f32_e32 v203, v203
	v_rcp_f32_e32 v204, v204
	v_rcp_f32_e32 v205, v205
	s_nop 0
	v_cvt_pk_bf16_f32 v206, v190, v191
	v_cvt_pk_bf16_f32 v207, v192, v193
	v_cvt_pk_bf16_f32 v208, v194, v195
	v_cvt_pk_bf16_f32 v209, v196, v197
	v_cvt_pk_bf16_f32 v210, v198, v199
	v_cvt_pk_bf16_f32 v211, v200, v201
	v_cvt_pk_bf16_f32 v212, v202, v203
	v_cvt_pk_bf16_f32 v213, v204, v205
	global_store_dwordx4 v[166:167], v[206:209], off
	global_store_dwordx4 v[166:167], v[210:213], off offset:64
	s_nop 1
	s_mov_b64 s[98:99], 0x20000
	v_lshl_add_u64 v[166:167], v[166:167], 0, s[98:99]
	v_pk_fma_f32 v[190:191], v[12:13], v[186:187], v[170:171]
	v_pk_fma_f32 v[192:193], v[14:15], v[186:187], v[172:173]
	v_pk_fma_f32 v[194:195], v[8:9], v[186:187], v[174:175]
	v_pk_fma_f32 v[196:197], v[10:11], v[186:187], v[176:177]
	v_pk_fma_f32 v[198:199], v[4:5], v[186:187], v[178:179]
	v_pk_fma_f32 v[200:201], v[6:7], v[186:187], v[180:181]
	v_pk_fma_f32 v[202:203], v[0:1], v[186:187], v[182:183]
	v_pk_fma_f32 v[204:205], v[2:3], v[186:187], v[184:185]
	v_exp_f32_e32 v190, v190
	v_exp_f32_e32 v191, v191
	v_exp_f32_e32 v192, v192
	v_exp_f32_e32 v193, v193
	v_exp_f32_e32 v194, v194
	v_exp_f32_e32 v195, v195
	v_exp_f32_e32 v196, v196
	v_exp_f32_e32 v197, v197
	v_exp_f32_e32 v198, v198
	v_exp_f32_e32 v199, v199
	v_exp_f32_e32 v200, v200
	v_exp_f32_e32 v201, v201
	v_exp_f32_e32 v202, v202
	v_exp_f32_e32 v203, v203
	v_exp_f32_e32 v204, v204
	v_exp_f32_e32 v205, v205
	s_nop 0
	v_pk_add_f32 v[190:191], v[190:191], v[188:189]
	v_pk_add_f32 v[192:193], v[192:193], v[188:189]
	v_pk_add_f32 v[194:195], v[194:195], v[188:189]
	v_pk_add_f32 v[196:197], v[196:197], v[188:189]
	v_pk_add_f32 v[198:199], v[198:199], v[188:189]
	v_pk_add_f32 v[200:201], v[200:201], v[188:189]
	v_pk_add_f32 v[202:203], v[202:203], v[188:189]
	v_pk_add_f32 v[204:205], v[204:205], v[188:189]
	v_rcp_f32_e32 v190, v190
	v_rcp_f32_e32 v191, v191
	v_rcp_f32_e32 v192, v192
	v_rcp_f32_e32 v193, v193
	v_rcp_f32_e32 v194, v194
	v_rcp_f32_e32 v195, v195
	v_rcp_f32_e32 v196, v196
	v_rcp_f32_e32 v197, v197
	v_rcp_f32_e32 v198, v198
	v_rcp_f32_e32 v199, v199
	v_rcp_f32_e32 v200, v200
	v_rcp_f32_e32 v201, v201
	v_rcp_f32_e32 v202, v202
	v_rcp_f32_e32 v203, v203
	v_rcp_f32_e32 v204, v204
	v_rcp_f32_e32 v205, v205
	s_nop 0
	v_cvt_pk_bf16_f32 v206, v190, v191
	v_cvt_pk_bf16_f32 v207, v192, v193
	v_cvt_pk_bf16_f32 v208, v194, v195
	v_cvt_pk_bf16_f32 v209, v196, v197
	v_cvt_pk_bf16_f32 v210, v198, v199
	v_cvt_pk_bf16_f32 v211, v200, v201
	v_cvt_pk_bf16_f32 v212, v202, v203
	v_cvt_pk_bf16_f32 v213, v204, v205
	global_store_dwordx4 v[166:167], v[206:209], off
	s_and_b64 vcc, exec, s[2:3]
	s_mov_b64 s[2:3], -1
	global_store_dwordx4 v[166:167], v[210:213], off offset:64
	s_cbranch_vccnz .LBB0_1091
	s_andn2_b64 vcc, exec, s[18:19]
	s_cbranch_vccnz .LBB0_1090
	s_barrier
	s_branch .LBB0_1090
